# baseline (speedup 1.0000x reference)
.LBB0_1489:
	v_lshl_add_u32 v140, s16, 8, v146
	v_ashrrev_i32_e32 v141, 31, v140
	v_lshl_add_u64 v[142:143], v[140:141], 3, s[46:47]
	global_load_dwordx2 v[150:151], v[142:143], off
	global_load_dwordx2 v[242:243], v[142:143], off offset:128
	global_load_dwordx2 v[244:245], v[142:143], off offset:256
	global_load_dwordx2 v[246:247], v[142:143], off offset:384
	global_load_dwordx2 v[248:249], v[142:143], off offset:1024
	global_load_dwordx2 v[250:251], v[142:143], off offset:1152
	global_load_dwordx2 v[252:253], v[142:143], off offset:1280
	global_load_dwordx2 v[254:255], v[142:143], off offset:1408
	v_readlane_b32 s6, v238, 62
	v_lshl_or_b32 v144, s14, 7, v148
	v_readlane_b32 s7, v238, 63
	v_ashrrev_i32_e32 v145, 31, v144
	s_mov_b64 s[28:29], s[34:35]
	s_waitcnt vmcnt(0)
	v_ffbh_u32_e32 v141, v151
	v_min_u32_e32 v141, 32, v141
	v_lshlrev_b64 v[150:151], v141, v[150:151]
	v_min_u32_e32 v150, 1, v150
	v_or_b32_e32 v150, v151, v150
	v_cvt_f32_u32_e32 v150, v150
	v_sub_u32_e32 v141, 32, v141
	v_ldexp_f32 v141, v150, v141
	v_fmamk_f32 v141, v141, 0x2e000000, v191
	v_cmp_gt_f32_e32 vcc, s58, v141
	v_mul_f32_e32 v150, 0x4b800000, v141
	s_nop 0
	v_cndmask_b32_e32 v141, v141, v150, vcc
	v_rsq_f32_e32 v141, v141
	s_nop 0
	v_mul_f32_e32 v150, 0x45800000, v141
	v_cndmask_b32_e32 v150, v141, v150, vcc
	v_pk_mul_f32 v[124:125], v[124:125], v[150:151] op_sel_hi:[1,0]
	v_pk_mul_f32 v[152:153], v[114:115], v[150:151] op_sel_hi:[1,0]
	v_pk_mul_f32 v[114:115], v[112:113], v[150:151] op_sel_hi:[1,0]
	v_mul_f32_e32 v112, 0xbfb8aa3b, v124
	v_mul_f32_e32 v113, 0xbfb8aa3b, v125
	v_exp_f32_e32 v112, v112
	v_exp_f32_e32 v113, v113
	v_pk_mul_f32 v[116:117], v[116:117], v[150:151] op_sel_hi:[1,0]
	v_pk_mul_f32 v[126:127], v[126:127], v[150:151] op_sel_hi:[1,0]
	v_add_f32_e32 v112, 1.0, v112
	v_add_f32_e32 v113, 1.0, v113
	v_rcp_f32_e32 v112, v112
	v_rcp_f32_e32 v113, v113
	v_pk_mul_f32 v[118:119], v[118:119], v[150:151] op_sel_hi:[1,0]
	v_pk_mul_f32 v[120:121], v[120:121], v[150:151] op_sel_hi:[1,0]
	v_pk_mul_f32 v[122:123], v[122:123], v[150:151] op_sel_hi:[1,0]
	v_pk_mul_f32 v[112:113], v[124:125], v[112:113]
	s_nop 0
	v_pk_mul_f32 v[112:113], v[116:117], v[112:113]
	s_nop 0
	v_cvt_pk_bf16_f32 v112, v112, v113
	v_mul_f32_e32 v113, 0xbfb8aa3b, v126
	v_exp_f32_e32 v113, v113
	s_nop 0
	v_add_f32_e32 v113, 1.0, v113
	v_rcp_f32_e32 v116, v113
	v_mul_f32_e32 v113, 0xbfb8aa3b, v127
	v_exp_f32_e32 v113, v113
	s_nop 0
	v_add_f32_e32 v113, 1.0, v113
	v_rcp_f32_e32 v117, v113
	s_nop 0
	v_pk_mul_f32 v[116:117], v[126:127], v[116:117]
	s_nop 0
	v_pk_mul_f32 v[116:117], v[118:119], v[116:117]
	v_lshlrev_b64 v[118:119], 1, v[144:145]
	v_cvt_pk_bf16_f32 v113, v116, v117
	v_mul_f32_e32 v116, 0xbfb8aa3b, v120
	v_mul_f32_e32 v117, 0xbfb8aa3b, v121
	v_exp_f32_e32 v116, v116
	v_exp_f32_e32 v117, v117
	v_add_f32_e32 v116, 1.0, v116
	v_add_f32_e32 v117, 1.0, v117
	v_rcp_f32_e32 v116, v116
	v_rcp_f32_e32 v117, v117
	s_nop 0
	v_pk_mul_f32 v[116:117], v[120:121], v[116:117]
	s_nop 0
	v_pk_mul_f32 v[114:115], v[114:115], v[116:117]
	s_nop 0
	v_cvt_pk_bf16_f32 v114, v114, v115
	v_mul_f32_e32 v115, 0xbfb8aa3b, v122
	v_exp_f32_e32 v115, v115
	s_nop 0
	v_add_f32_e32 v115, 1.0, v115
	v_rcp_f32_e32 v116, v115
	v_mul_f32_e32 v115, 0xbfb8aa3b, v123
	v_exp_f32_e32 v115, v115
	s_nop 0
	v_add_f32_e32 v115, 1.0, v115
	v_rcp_f32_e32 v117, v115
	s_nop 0
	v_pk_mul_f32 v[116:117], v[122:123], v[116:117]
	s_nop 0
	v_pk_mul_f32 v[116:117], v[152:153], v[116:117]
	s_nop 0
	v_cvt_pk_bf16_f32 v115, v116, v117
	v_mov_b64_e32 v[116:117], s[6:7]
	v_mad_i64_i32 v[120:121], s[6:7], v140, s69, v[116:117]
	v_lshl_add_u64 v[120:121], v[120:121], 0, v[118:119]
	global_store_dwordx4 v[120:121], v[112:115], off
	s_nop 1
	v_or_b32_e32 v112, 16, v140
	v_ashrrev_i32_e32 v113, 31, v112
	v_lshl_add_u64 v[114:115], v[112:113], 3, s[46:47]
	s_nop 1
	v_ffbh_u32_e32 v113, v243
	v_min_u32_e32 v113, 32, v113
	v_lshlrev_b64 v[114:115], v113, v[242:243]
	v_min_u32_e32 v114, 1, v114
	v_or_b32_e32 v114, v115, v114
	v_cvt_f32_u32_e32 v114, v114
	v_sub_u32_e32 v113, 32, v113
	v_ldexp_f32 v113, v114, v113
	v_fmamk_f32 v113, v113, 0x2e000000, v191
	v_cmp_gt_f32_e32 vcc, s58, v113
	v_mul_f32_e32 v114, 0x4b800000, v113
	s_nop 0
	v_cndmask_b32_e32 v113, v113, v114, vcc
	v_rsq_f32_e32 v113, v113
	s_nop 0
	v_mul_f32_e32 v114, 0x45800000, v113
	v_cndmask_b32_e32 v114, v113, v114, vcc
	v_pk_mul_f32 v[108:109], v[108:109], v[114:115] op_sel_hi:[1,0]
	v_pk_mul_f32 v[120:121], v[98:99], v[114:115] op_sel_hi:[1,0]
	v_pk_mul_f32 v[98:99], v[96:97], v[114:115] op_sel_hi:[1,0]
	v_mul_f32_e32 v96, 0xbfb8aa3b, v108
	v_mul_f32_e32 v97, 0xbfb8aa3b, v109
	v_exp_f32_e32 v96, v96
	v_exp_f32_e32 v97, v97
	v_pk_mul_f32 v[100:101], v[100:101], v[114:115] op_sel_hi:[1,0]
	v_pk_mul_f32 v[110:111], v[110:111], v[114:115] op_sel_hi:[1,0]
	v_add_f32_e32 v96, 1.0, v96
	v_add_f32_e32 v97, 1.0, v97
	v_rcp_f32_e32 v96, v96
	v_rcp_f32_e32 v97, v97
	v_pk_mul_f32 v[102:103], v[102:103], v[114:115] op_sel_hi:[1,0]
	v_pk_mul_f32 v[104:105], v[104:105], v[114:115] op_sel_hi:[1,0]
	v_pk_mul_f32 v[106:107], v[106:107], v[114:115] op_sel_hi:[1,0]
	v_pk_mul_f32 v[96:97], v[108:109], v[96:97]
	s_nop 0
	v_pk_mul_f32 v[96:97], v[100:101], v[96:97]
	s_nop 0
	v_cvt_pk_bf16_f32 v96, v96, v97
	v_mul_f32_e32 v97, 0xbfb8aa3b, v110
	v_exp_f32_e32 v97, v97
	s_nop 0
	v_add_f32_e32 v97, 1.0, v97
	v_rcp_f32_e32 v100, v97
	v_mul_f32_e32 v97, 0xbfb8aa3b, v111
	v_exp_f32_e32 v97, v97
	s_nop 0
	v_add_f32_e32 v97, 1.0, v97
	v_rcp_f32_e32 v101, v97
	s_nop 0
	v_pk_mul_f32 v[100:101], v[110:111], v[100:101]
	s_nop 0
	v_pk_mul_f32 v[100:101], v[102:103], v[100:101]
	s_nop 0
	v_cvt_pk_bf16_f32 v97, v100, v101
	v_mul_f32_e32 v100, 0xbfb8aa3b, v104
	v_mul_f32_e32 v101, 0xbfb8aa3b, v105
	v_exp_f32_e32 v100, v100
	v_exp_f32_e32 v101, v101
	v_add_f32_e32 v100, 1.0, v100
	v_add_f32_e32 v101, 1.0, v101
	v_rcp_f32_e32 v100, v100
	v_rcp_f32_e32 v101, v101
	s_nop 0
	v_pk_mul_f32 v[100:101], v[104:105], v[100:101]
	s_nop 0
	v_pk_mul_f32 v[98:99], v[98:99], v[100:101]
	s_nop 0
	v_cvt_pk_bf16_f32 v98, v98, v99
	v_mul_f32_e32 v99, 0xbfb8aa3b, v106
	v_exp_f32_e32 v99, v99
	s_nop 0
	v_add_f32_e32 v99, 1.0, v99
	v_rcp_f32_e32 v100, v99
	v_mul_f32_e32 v99, 0xbfb8aa3b, v107
	v_exp_f32_e32 v99, v99
	s_nop 0
	v_add_f32_e32 v99, 1.0, v99
	v_rcp_f32_e32 v101, v99
	s_nop 0
	v_pk_mul_f32 v[100:101], v[106:107], v[100:101]
	s_nop 0
	v_pk_mul_f32 v[100:101], v[120:121], v[100:101]
	s_nop 0
	v_cvt_pk_bf16_f32 v99, v100, v101
	v_mad_i64_i32 v[100:101], s[6:7], v112, s69, v[116:117]
	v_lshl_add_u64 v[100:101], v[100:101], 0, v[118:119]
	global_store_dwordx4 v[100:101], v[96:99], off
	s_nop 1
	v_or_b32_e32 v96, 32, v140
	v_ashrrev_i32_e32 v97, 31, v96
	v_lshl_add_u64 v[98:99], v[96:97], 3, s[46:47]
	s_nop 1
	v_ffbh_u32_e32 v97, v245
	v_min_u32_e32 v97, 32, v97
	v_lshlrev_b64 v[98:99], v97, v[244:245]
	v_min_u32_e32 v98, 1, v98
	v_or_b32_e32 v98, v99, v98
	v_cvt_f32_u32_e32 v98, v98
	v_sub_u32_e32 v97, 32, v97
	v_ldexp_f32 v97, v98, v97
	v_fmamk_f32 v97, v97, 0x2e000000, v191
	v_cmp_gt_f32_e32 vcc, s58, v97
	v_mul_f32_e32 v98, 0x4b800000, v97
	s_nop 0
	v_cndmask_b32_e32 v97, v97, v98, vcc
	v_rsq_f32_e32 v97, v97
	s_nop 0
	v_mul_f32_e32 v98, 0x45800000, v97
	v_cndmask_b32_e32 v98, v97, v98, vcc
	v_pk_mul_f32 v[92:93], v[92:93], v[98:99] op_sel_hi:[1,0]
	v_pk_mul_f32 v[100:101], v[82:83], v[98:99] op_sel_hi:[1,0]
	v_pk_mul_f32 v[82:83], v[80:81], v[98:99] op_sel_hi:[1,0]
	v_mul_f32_e32 v80, 0xbfb8aa3b, v92
	v_mul_f32_e32 v81, 0xbfb8aa3b, v93
	v_exp_f32_e32 v80, v80
	v_exp_f32_e32 v81, v81
	v_pk_mul_f32 v[84:85], v[84:85], v[98:99] op_sel_hi:[1,0]
	v_pk_mul_f32 v[94:95], v[94:95], v[98:99] op_sel_hi:[1,0]
	v_add_f32_e32 v80, 1.0, v80
	v_add_f32_e32 v81, 1.0, v81
	v_rcp_f32_e32 v80, v80
	v_rcp_f32_e32 v81, v81
	v_pk_mul_f32 v[86:87], v[86:87], v[98:99] op_sel_hi:[1,0]
	v_pk_mul_f32 v[88:89], v[88:89], v[98:99] op_sel_hi:[1,0]
	v_pk_mul_f32 v[90:91], v[90:91], v[98:99] op_sel_hi:[1,0]
	v_pk_mul_f32 v[80:81], v[92:93], v[80:81]
	s_nop 0
	v_pk_mul_f32 v[80:81], v[84:85], v[80:81]
	s_nop 0
	v_cvt_pk_bf16_f32 v80, v80, v81
	v_mul_f32_e32 v81, 0xbfb8aa3b, v94
	v_exp_f32_e32 v81, v81
	s_nop 0
	v_add_f32_e32 v81, 1.0, v81
	v_rcp_f32_e32 v84, v81
	v_mul_f32_e32 v81, 0xbfb8aa3b, v95
	v_exp_f32_e32 v81, v81
	s_nop 0
	v_add_f32_e32 v81, 1.0, v81
	v_rcp_f32_e32 v85, v81
	s_nop 0
	v_pk_mul_f32 v[84:85], v[94:95], v[84:85]
	s_nop 0
	v_pk_mul_f32 v[84:85], v[86:87], v[84:85]
	s_nop 0
	v_cvt_pk_bf16_f32 v81, v84, v85
	v_mul_f32_e32 v84, 0xbfb8aa3b, v88
	v_mul_f32_e32 v85, 0xbfb8aa3b, v89
	v_exp_f32_e32 v84, v84
	v_exp_f32_e32 v85, v85
	v_add_f32_e32 v84, 1.0, v84
	v_add_f32_e32 v85, 1.0, v85
	v_rcp_f32_e32 v84, v84
	v_rcp_f32_e32 v85, v85
	s_nop 0
	v_pk_mul_f32 v[84:85], v[88:89], v[84:85]
	s_nop 0
	v_pk_mul_f32 v[82:83], v[82:83], v[84:85]
	s_nop 0
	v_cvt_pk_bf16_f32 v82, v82, v83
	v_mul_f32_e32 v83, 0xbfb8aa3b, v90
	v_exp_f32_e32 v83, v83
	s_nop 0
	v_add_f32_e32 v83, 1.0, v83
	v_rcp_f32_e32 v84, v83
	v_mul_f32_e32 v83, 0xbfb8aa3b, v91
	v_exp_f32_e32 v83, v83
	s_nop 0
	v_add_f32_e32 v83, 1.0, v83
	v_rcp_f32_e32 v85, v83
	s_nop 0
	v_pk_mul_f32 v[84:85], v[90:91], v[84:85]
	s_nop 0
	v_pk_mul_f32 v[84:85], v[100:101], v[84:85]
	s_nop 0
	v_cvt_pk_bf16_f32 v83, v84, v85
	v_mad_i64_i32 v[84:85], s[6:7], v96, s69, v[116:117]
	v_lshl_add_u64 v[84:85], v[84:85], 0, v[118:119]
	global_store_dwordx4 v[84:85], v[80:83], off
	s_nop 1
	v_or_b32_e32 v80, 48, v140
	v_ashrrev_i32_e32 v81, 31, v80
	v_lshl_add_u64 v[82:83], v[80:81], 3, s[46:47]
	s_nop 1
	v_ffbh_u32_e32 v81, v247
	v_min_u32_e32 v81, 32, v81
	v_lshlrev_b64 v[82:83], v81, v[246:247]
	v_min_u32_e32 v82, 1, v82
	v_or_b32_e32 v82, v83, v82
	v_cvt_f32_u32_e32 v82, v82
	v_sub_u32_e32 v81, 32, v81
	v_ldexp_f32 v81, v82, v81
	v_fmamk_f32 v81, v81, 0x2e000000, v191
	v_cmp_gt_f32_e32 vcc, s58, v81
	v_mul_f32_e32 v82, 0x4b800000, v81
	s_nop 0
	v_cndmask_b32_e32 v81, v81, v82, vcc
	v_rsq_f32_e32 v81, v81
	s_nop 0
	v_mul_f32_e32 v82, 0x45800000, v81
	v_cndmask_b32_e32 v82, v81, v82, vcc
	v_pk_mul_f32 v[76:77], v[76:77], v[82:83] op_sel_hi:[1,0]
	v_pk_mul_f32 v[84:85], v[66:67], v[82:83] op_sel_hi:[1,0]
	v_pk_mul_f32 v[66:67], v[64:65], v[82:83] op_sel_hi:[1,0]
	v_mul_f32_e32 v64, 0xbfb8aa3b, v76
	v_mul_f32_e32 v65, 0xbfb8aa3b, v77
	v_exp_f32_e32 v64, v64
	v_exp_f32_e32 v65, v65
	v_pk_mul_f32 v[68:69], v[68:69], v[82:83] op_sel_hi:[1,0]
	v_pk_mul_f32 v[78:79], v[78:79], v[82:83] op_sel_hi:[1,0]
	v_add_f32_e32 v64, 1.0, v64
	v_add_f32_e32 v65, 1.0, v65
	v_rcp_f32_e32 v64, v64
	v_rcp_f32_e32 v65, v65
	v_pk_mul_f32 v[70:71], v[70:71], v[82:83] op_sel_hi:[1,0]
	v_pk_mul_f32 v[72:73], v[72:73], v[82:83] op_sel_hi:[1,0]
	v_pk_mul_f32 v[74:75], v[74:75], v[82:83] op_sel_hi:[1,0]
	v_pk_mul_f32 v[64:65], v[76:77], v[64:65]
	s_nop 0
	v_pk_mul_f32 v[64:65], v[68:69], v[64:65]
	s_nop 0
	v_cvt_pk_bf16_f32 v64, v64, v65
	v_mul_f32_e32 v65, 0xbfb8aa3b, v78
	v_exp_f32_e32 v65, v65
	s_nop 0
	v_add_f32_e32 v65, 1.0, v65
	v_rcp_f32_e32 v68, v65
	v_mul_f32_e32 v65, 0xbfb8aa3b, v79
	v_exp_f32_e32 v65, v65
	s_nop 0
	v_add_f32_e32 v65, 1.0, v65
	v_rcp_f32_e32 v69, v65
	s_nop 0
	v_pk_mul_f32 v[68:69], v[78:79], v[68:69]
	s_nop 0
	v_pk_mul_f32 v[68:69], v[70:71], v[68:69]
	s_nop 0
	v_cvt_pk_bf16_f32 v65, v68, v69
	v_mul_f32_e32 v68, 0xbfb8aa3b, v72
	v_mul_f32_e32 v69, 0xbfb8aa3b, v73
	v_exp_f32_e32 v68, v68
	v_exp_f32_e32 v69, v69
	v_add_f32_e32 v68, 1.0, v68
	v_add_f32_e32 v69, 1.0, v69
	v_rcp_f32_e32 v68, v68
	v_rcp_f32_e32 v69, v69
	s_nop 0
	v_pk_mul_f32 v[68:69], v[72:73], v[68:69]
	s_nop 0
	v_pk_mul_f32 v[66:67], v[66:67], v[68:69]
	s_nop 0
	v_cvt_pk_bf16_f32 v66, v66, v67
	v_mul_f32_e32 v67, 0xbfb8aa3b, v74
	v_exp_f32_e32 v67, v67
	s_nop 0
	v_add_f32_e32 v67, 1.0, v67
	v_rcp_f32_e32 v68, v67
	v_mul_f32_e32 v67, 0xbfb8aa3b, v75
	v_exp_f32_e32 v67, v67
	s_nop 0
	v_add_f32_e32 v67, 1.0, v67
	v_rcp_f32_e32 v69, v67
	s_nop 0
	v_pk_mul_f32 v[68:69], v[74:75], v[68:69]
	s_nop 0
	v_pk_mul_f32 v[68:69], v[84:85], v[68:69]
	s_nop 0
	v_cvt_pk_bf16_f32 v67, v68, v69
	v_mad_i64_i32 v[68:69], s[6:7], v80, s69, v[116:117]
	v_lshl_add_u64 v[68:69], v[68:69], 0, v[118:119]
	global_store_dwordx4 v[68:69], v[64:67], off
	v_add_u32_e32 v68, 0x80, v140
	s_nop 1
	v_ffbh_u32_e32 v66, v249
	v_min_u32_e32 v66, 32, v66
	v_lshlrev_b64 v[64:65], v66, v[248:249]
	v_min_u32_e32 v64, 1, v64
	v_or_b32_e32 v64, v65, v64
	v_cvt_f32_u32_e32 v64, v64
	v_sub_u32_e32 v65, 32, v66
	v_ldexp_f32 v64, v64, v65
	v_fmamk_f32 v64, v64, 0x2e000000, v191
	v_cmp_gt_f32_e32 vcc, s58, v64
	v_mul_f32_e32 v65, 0x4b800000, v64
	s_nop 0
	v_cndmask_b32_e32 v64, v64, v65, vcc
	v_rsq_f32_e32 v64, v64
	s_nop 0
	v_mul_f32_e32 v65, 0x45800000, v64
	v_cndmask_b32_e32 v64, v64, v65, vcc
	v_pk_mul_f32 v[60:61], v[60:61], v[64:65] op_sel_hi:[1,0]
	v_pk_mul_f32 v[66:67], v[50:51], v[64:65] op_sel_hi:[1,0]
	v_pk_mul_f32 v[50:51], v[48:49], v[64:65] op_sel_hi:[1,0]
	v_mul_f32_e32 v48, 0xbfb8aa3b, v60
	v_mul_f32_e32 v49, 0xbfb8aa3b, v61
	v_exp_f32_e32 v48, v48
	v_exp_f32_e32 v49, v49
	v_pk_mul_f32 v[52:53], v[52:53], v[64:65] op_sel_hi:[1,0]
	v_pk_mul_f32 v[62:63], v[62:63], v[64:65] op_sel_hi:[1,0]
	v_add_f32_e32 v48, 1.0, v48
	v_add_f32_e32 v49, 1.0, v49
	v_rcp_f32_e32 v48, v48
	v_rcp_f32_e32 v49, v49
	v_pk_mul_f32 v[54:55], v[54:55], v[64:65] op_sel_hi:[1,0]
	v_pk_mul_f32 v[56:57], v[56:57], v[64:65] op_sel_hi:[1,0]
	v_pk_mul_f32 v[58:59], v[58:59], v[64:65] op_sel_hi:[1,0]
	v_pk_mul_f32 v[48:49], v[60:61], v[48:49]
	s_nop 0
	v_pk_mul_f32 v[48:49], v[52:53], v[48:49]
	s_nop 0
	v_cvt_pk_bf16_f32 v48, v48, v49
	v_mul_f32_e32 v49, 0xbfb8aa3b, v62
	v_exp_f32_e32 v49, v49
	s_nop 0
	v_add_f32_e32 v49, 1.0, v49
	v_rcp_f32_e32 v52, v49
	v_mul_f32_e32 v49, 0xbfb8aa3b, v63
	v_exp_f32_e32 v49, v49
	s_nop 0
	v_add_f32_e32 v49, 1.0, v49
	v_rcp_f32_e32 v53, v49
	s_nop 0
	v_pk_mul_f32 v[52:53], v[62:63], v[52:53]
	s_nop 0
	v_pk_mul_f32 v[52:53], v[54:55], v[52:53]
	s_nop 0
	v_cvt_pk_bf16_f32 v49, v52, v53
	v_mul_f32_e32 v52, 0xbfb8aa3b, v56
	v_mul_f32_e32 v53, 0xbfb8aa3b, v57
	v_exp_f32_e32 v52, v52
	v_exp_f32_e32 v53, v53
	v_add_f32_e32 v52, 1.0, v52
	v_add_f32_e32 v53, 1.0, v53
	v_rcp_f32_e32 v52, v52
	v_rcp_f32_e32 v53, v53
	s_nop 0
	v_pk_mul_f32 v[52:53], v[56:57], v[52:53]
	s_nop 0
	v_pk_mul_f32 v[50:51], v[50:51], v[52:53]
	s_nop 0
	v_cvt_pk_bf16_f32 v50, v50, v51
	v_mul_f32_e32 v51, 0xbfb8aa3b, v58
	v_exp_f32_e32 v51, v51
	s_nop 0
	v_add_f32_e32 v51, 1.0, v51
	v_rcp_f32_e32 v52, v51
	v_mul_f32_e32 v51, 0xbfb8aa3b, v59
	v_exp_f32_e32 v51, v51
	s_nop 0
	v_add_f32_e32 v51, 1.0, v51
	v_rcp_f32_e32 v53, v51
	s_nop 0
	v_pk_mul_f32 v[52:53], v[58:59], v[52:53]
	s_nop 0
	v_pk_mul_f32 v[52:53], v[66:67], v[52:53]
	s_nop 0
	v_cvt_pk_bf16_f32 v51, v52, v53
	v_mad_i64_i32 v[52:53], s[6:7], v68, s69, v[116:117]
	v_lshl_add_u64 v[52:53], v[52:53], 0, v[118:119]
	global_store_dwordx4 v[52:53], v[48:51], off
	v_add_u32_e32 v52, 0x90, v140
	s_nop 1
	v_ffbh_u32_e32 v50, v251
	v_min_u32_e32 v50, 32, v50
	v_lshlrev_b64 v[48:49], v50, v[250:251]
	v_min_u32_e32 v48, 1, v48
	v_or_b32_e32 v48, v49, v48
	v_cvt_f32_u32_e32 v48, v48
	v_sub_u32_e32 v49, 32, v50
	v_ldexp_f32 v48, v48, v49
	v_fmamk_f32 v48, v48, 0x2e000000, v191
	v_cmp_gt_f32_e32 vcc, s58, v48
	v_mul_f32_e32 v49, 0x4b800000, v48
	s_nop 0
	v_cndmask_b32_e32 v48, v48, v49, vcc
	v_rsq_f32_e32 v48, v48
	s_nop 0
	v_mul_f32_e32 v49, 0x45800000, v48
	v_cndmask_b32_e32 v48, v48, v49, vcc
	v_pk_mul_f32 v[44:45], v[44:45], v[48:49] op_sel_hi:[1,0]
	v_pk_mul_f32 v[50:51], v[34:35], v[48:49] op_sel_hi:[1,0]
	v_pk_mul_f32 v[34:35], v[32:33], v[48:49] op_sel_hi:[1,0]
	v_mul_f32_e32 v32, 0xbfb8aa3b, v44
	v_mul_f32_e32 v33, 0xbfb8aa3b, v45
	v_exp_f32_e32 v32, v32
	v_exp_f32_e32 v33, v33
	v_pk_mul_f32 v[36:37], v[36:37], v[48:49] op_sel_hi:[1,0]
	v_pk_mul_f32 v[46:47], v[46:47], v[48:49] op_sel_hi:[1,0]
	v_add_f32_e32 v32, 1.0, v32
	v_add_f32_e32 v33, 1.0, v33
	v_rcp_f32_e32 v32, v32
	v_rcp_f32_e32 v33, v33
	v_pk_mul_f32 v[38:39], v[38:39], v[48:49] op_sel_hi:[1,0]
	v_pk_mul_f32 v[40:41], v[40:41], v[48:49] op_sel_hi:[1,0]
	v_pk_mul_f32 v[42:43], v[42:43], v[48:49] op_sel_hi:[1,0]
	v_pk_mul_f32 v[32:33], v[44:45], v[32:33]
	s_nop 0
	v_pk_mul_f32 v[32:33], v[36:37], v[32:33]
	s_nop 0
	v_cvt_pk_bf16_f32 v32, v32, v33
	v_mul_f32_e32 v33, 0xbfb8aa3b, v46
	v_exp_f32_e32 v33, v33
	s_nop 0
	v_add_f32_e32 v33, 1.0, v33
	v_rcp_f32_e32 v36, v33
	v_mul_f32_e32 v33, 0xbfb8aa3b, v47
	v_exp_f32_e32 v33, v33
	s_nop 0
	v_add_f32_e32 v33, 1.0, v33
	v_rcp_f32_e32 v37, v33
	s_nop 0
	v_pk_mul_f32 v[36:37], v[46:47], v[36:37]
	s_nop 0
	v_pk_mul_f32 v[36:37], v[38:39], v[36:37]
	s_nop 0
	v_cvt_pk_bf16_f32 v33, v36, v37
	v_mul_f32_e32 v36, 0xbfb8aa3b, v40
	v_mul_f32_e32 v37, 0xbfb8aa3b, v41
	v_exp_f32_e32 v36, v36
	v_exp_f32_e32 v37, v37
	v_add_f32_e32 v36, 1.0, v36
	v_add_f32_e32 v37, 1.0, v37
	v_rcp_f32_e32 v36, v36
	v_rcp_f32_e32 v37, v37
	s_nop 0
	v_pk_mul_f32 v[36:37], v[40:41], v[36:37]
	s_nop 0
	v_pk_mul_f32 v[34:35], v[34:35], v[36:37]
	s_nop 0
	v_cvt_pk_bf16_f32 v34, v34, v35
	v_mul_f32_e32 v35, 0xbfb8aa3b, v42
	v_exp_f32_e32 v35, v35
	s_nop 0
	v_add_f32_e32 v35, 1.0, v35
	v_rcp_f32_e32 v36, v35
	v_mul_f32_e32 v35, 0xbfb8aa3b, v43
	v_exp_f32_e32 v35, v35
	s_nop 0
	v_add_f32_e32 v35, 1.0, v35
	v_rcp_f32_e32 v37, v35
	s_nop 0
	v_pk_mul_f32 v[36:37], v[42:43], v[36:37]
	s_nop 0
	v_pk_mul_f32 v[36:37], v[50:51], v[36:37]
	s_nop 0
	v_cvt_pk_bf16_f32 v35, v36, v37
	v_mad_i64_i32 v[36:37], s[6:7], v52, s69, v[116:117]
	v_lshl_add_u64 v[36:37], v[36:37], 0, v[118:119]
	global_store_dwordx4 v[36:37], v[32:35], off
	v_add_u32_e32 v36, 0xa0, v140
	s_nop 1
	v_ffbh_u32_e32 v34, v253
	v_min_u32_e32 v34, 32, v34
	v_lshlrev_b64 v[32:33], v34, v[252:253]
	v_min_u32_e32 v32, 1, v32
	v_or_b32_e32 v32, v33, v32
	v_cvt_f32_u32_e32 v32, v32
	v_sub_u32_e32 v33, 32, v34
	v_ldexp_f32 v32, v32, v33
	v_fmamk_f32 v32, v32, 0x2e000000, v191
	v_cmp_gt_f32_e32 vcc, s58, v32
	v_mul_f32_e32 v33, 0x4b800000, v32
	s_nop 0
	v_cndmask_b32_e32 v32, v32, v33, vcc
	v_rsq_f32_e32 v32, v32
	s_nop 0
	v_mul_f32_e32 v33, 0x45800000, v32
	v_cndmask_b32_e32 v32, v32, v33, vcc
	v_pk_mul_f32 v[28:29], v[28:29], v[32:33] op_sel_hi:[1,0]
	v_pk_mul_f32 v[34:35], v[18:19], v[32:33] op_sel_hi:[1,0]
	v_pk_mul_f32 v[18:19], v[16:17], v[32:33] op_sel_hi:[1,0]
	v_mul_f32_e32 v16, 0xbfb8aa3b, v28
	v_mul_f32_e32 v17, 0xbfb8aa3b, v29
	v_exp_f32_e32 v16, v16
	v_exp_f32_e32 v17, v17
	v_pk_mul_f32 v[20:21], v[20:21], v[32:33] op_sel_hi:[1,0]
	v_pk_mul_f32 v[30:31], v[30:31], v[32:33] op_sel_hi:[1,0]
	v_add_f32_e32 v16, 1.0, v16
	v_add_f32_e32 v17, 1.0, v17
	v_rcp_f32_e32 v16, v16
	v_rcp_f32_e32 v17, v17
	v_pk_mul_f32 v[22:23], v[22:23], v[32:33] op_sel_hi:[1,0]
	v_pk_mul_f32 v[24:25], v[24:25], v[32:33] op_sel_hi:[1,0]
	v_pk_mul_f32 v[26:27], v[26:27], v[32:33] op_sel_hi:[1,0]
	v_pk_mul_f32 v[16:17], v[28:29], v[16:17]
	s_nop 0
	v_pk_mul_f32 v[16:17], v[20:21], v[16:17]
	s_nop 0
	v_cvt_pk_bf16_f32 v16, v16, v17
	v_mul_f32_e32 v17, 0xbfb8aa3b, v30
	v_exp_f32_e32 v17, v17
	s_nop 0
	v_add_f32_e32 v17, 1.0, v17
	v_rcp_f32_e32 v20, v17
	v_mul_f32_e32 v17, 0xbfb8aa3b, v31
	v_exp_f32_e32 v17, v17
	s_nop 0
	v_add_f32_e32 v17, 1.0, v17
	v_rcp_f32_e32 v21, v17
	s_nop 0
	v_pk_mul_f32 v[20:21], v[30:31], v[20:21]
	s_nop 0
	v_pk_mul_f32 v[20:21], v[22:23], v[20:21]
	s_nop 0
	v_cvt_pk_bf16_f32 v17, v20, v21
	v_mul_f32_e32 v20, 0xbfb8aa3b, v24
	v_mul_f32_e32 v21, 0xbfb8aa3b, v25
	v_exp_f32_e32 v20, v20
	v_exp_f32_e32 v21, v21
	v_add_f32_e32 v20, 1.0, v20
	v_add_f32_e32 v21, 1.0, v21
	v_rcp_f32_e32 v20, v20
	v_rcp_f32_e32 v21, v21
	s_nop 0
	v_pk_mul_f32 v[20:21], v[24:25], v[20:21]
	s_nop 0
	v_pk_mul_f32 v[18:19], v[18:19], v[20:21]
	s_nop 0
	v_cvt_pk_bf16_f32 v18, v18, v19
	v_mul_f32_e32 v19, 0xbfb8aa3b, v26
	v_exp_f32_e32 v19, v19
	s_nop 0
	v_add_f32_e32 v19, 1.0, v19
	v_rcp_f32_e32 v20, v19
	v_mul_f32_e32 v19, 0xbfb8aa3b, v27
	v_exp_f32_e32 v19, v19
	s_nop 0
	v_add_f32_e32 v19, 1.0, v19
	v_rcp_f32_e32 v21, v19
	s_nop 0
	v_pk_mul_f32 v[20:21], v[26:27], v[20:21]
	s_nop 0
	v_pk_mul_f32 v[20:21], v[34:35], v[20:21]
	s_nop 0
	v_cvt_pk_bf16_f32 v19, v20, v21
	v_mad_i64_i32 v[20:21], s[6:7], v36, s69, v[116:117]
	v_lshl_add_u64 v[20:21], v[20:21], 0, v[118:119]
	global_store_dwordx4 v[20:21], v[16:19], off
	v_add_u32_e32 v20, 0xb0, v140
	s_nop 1
	v_ffbh_u32_e32 v18, v255
	v_min_u32_e32 v18, 32, v18
	v_lshlrev_b64 v[16:17], v18, v[254:255]
	v_min_u32_e32 v16, 1, v16
	v_or_b32_e32 v16, v17, v16
	v_cvt_f32_u32_e32 v16, v16
	v_sub_u32_e32 v17, 32, v18
	v_ldexp_f32 v16, v16, v17
	v_fmamk_f32 v16, v16, 0x2e000000, v191
	v_cmp_gt_f32_e32 vcc, s58, v16
	v_mul_f32_e32 v17, 0x4b800000, v16
	s_nop 0
	v_cndmask_b32_e32 v16, v16, v17, vcc
	v_rsq_f32_e32 v16, v16
	s_nop 0
	v_mul_f32_e32 v17, 0x45800000, v16
	v_cndmask_b32_e32 v16, v16, v17, vcc
	v_pk_mul_f32 v[12:13], v[12:13], v[16:17] op_sel_hi:[1,0]
	v_pk_mul_f32 v[18:19], v[2:3], v[16:17] op_sel_hi:[1,0]
	v_pk_mul_f32 v[2:3], v[0:1], v[16:17] op_sel_hi:[1,0]
	v_mul_f32_e32 v0, 0xbfb8aa3b, v12
	v_mul_f32_e32 v1, 0xbfb8aa3b, v13
	v_exp_f32_e32 v0, v0
	v_exp_f32_e32 v1, v1
	v_pk_mul_f32 v[4:5], v[4:5], v[16:17] op_sel_hi:[1,0]
	v_pk_mul_f32 v[14:15], v[14:15], v[16:17] op_sel_hi:[1,0]
	v_add_f32_e32 v0, 1.0, v0
	v_add_f32_e32 v1, 1.0, v1
	v_rcp_f32_e32 v0, v0
	v_rcp_f32_e32 v1, v1
	v_pk_mul_f32 v[6:7], v[6:7], v[16:17] op_sel_hi:[1,0]
	v_pk_mul_f32 v[8:9], v[8:9], v[16:17] op_sel_hi:[1,0]
	v_pk_mul_f32 v[10:11], v[10:11], v[16:17] op_sel_hi:[1,0]
	v_pk_mul_f32 v[0:1], v[12:13], v[0:1]
	s_andn2_b64 vcc, exec, s[40:41]
	v_pk_mul_f32 v[0:1], v[4:5], v[0:1]
	s_nop 0
	v_cvt_pk_bf16_f32 v0, v0, v1
	v_mul_f32_e32 v1, 0xbfb8aa3b, v14
	v_exp_f32_e32 v1, v1
	s_nop 0
	v_add_f32_e32 v1, 1.0, v1
	v_rcp_f32_e32 v4, v1
	v_mul_f32_e32 v1, 0xbfb8aa3b, v15
	v_exp_f32_e32 v1, v1
	s_nop 0
	v_add_f32_e32 v1, 1.0, v1
	v_rcp_f32_e32 v5, v1
	s_nop 0
	v_pk_mul_f32 v[4:5], v[14:15], v[4:5]
	s_nop 0
	v_pk_mul_f32 v[4:5], v[6:7], v[4:5]
	s_nop 0
	v_cvt_pk_bf16_f32 v1, v4, v5
	v_mul_f32_e32 v4, 0xbfb8aa3b, v8
	v_mul_f32_e32 v5, 0xbfb8aa3b, v9
	v_exp_f32_e32 v4, v4
	v_exp_f32_e32 v5, v5
	v_add_f32_e32 v4, 1.0, v4
	v_add_f32_e32 v5, 1.0, v5
	v_rcp_f32_e32 v4, v4
	v_rcp_f32_e32 v5, v5
	s_nop 0
	v_pk_mul_f32 v[4:5], v[8:9], v[4:5]
	s_nop 0
	v_pk_mul_f32 v[2:3], v[2:3], v[4:5]
	s_nop 0
	v_cvt_pk_bf16_f32 v2, v2, v3
	v_mul_f32_e32 v3, 0xbfb8aa3b, v10
	v_exp_f32_e32 v3, v3
	s_nop 0
	v_add_f32_e32 v3, 1.0, v3
	v_rcp_f32_e32 v4, v3
	v_mul_f32_e32 v3, 0xbfb8aa3b, v11
	v_exp_f32_e32 v3, v3
	s_nop 0
	v_add_f32_e32 v3, 1.0, v3
	v_rcp_f32_e32 v5, v3
	s_nop 0
	v_pk_mul_f32 v[4:5], v[10:11], v[4:5]
	s_nop 0
	v_pk_mul_f32 v[4:5], v[18:19], v[4:5]
	s_nop 0
	v_cvt_pk_bf16_f32 v3, v4, v5
	v_mad_i64_i32 v[4:5], s[6:7], v20, s69, v[116:117]
	v_lshl_add_u64 v[4:5], v[4:5], 0, v[118:119]
	s_mov_b64 s[6:7], -1
	global_store_dwordx4 v[4:5], v[0:3], off
	s_cbranch_vccnz .LBB0_1482
	s_andn2_b64 vcc, exec, s[38:39]
	s_cbranch_vccnz .LBB0_1481
	s_barrier
	s_branch .LBB0_1481

	.amdhsa_kernel _Z8yoco_fwd6Params
		.amdhsa_group_segment_fixed_size 0
		.amdhsa_private_segment_fixed_size 0
		.amdhsa_kernarg_size 504
		.amdhsa_user_sgpr_count 2
		.amdhsa_user_sgpr_dispatch_ptr 0
		.amdhsa_user_sgpr_queue_ptr 0
		.amdhsa_user_sgpr_kernarg_segment_ptr 1
		.amdhsa_user_sgpr_dispatch_id 0
		.amdhsa_user_sgpr_kernarg_preload_length 0
		.amdhsa_user_sgpr_kernarg_preload_offset 0
		.amdhsa_user_sgpr_private_segment_size 0
		.amdhsa_uses_dynamic_stack 0
		.amdhsa_enable_private_segment 0
		.amdhsa_system_sgpr_workgroup_id_x 1
		.amdhsa_system_sgpr_workgroup_id_y 0
		.amdhsa_system_sgpr_workgroup_id_z 0
		.amdhsa_system_sgpr_workgroup_info 0
		.amdhsa_system_vgpr_workitem_id 2
		.amdhsa_next_free_vgpr 256
		.amdhsa_next_free_sgpr 100
		.amdhsa_accum_offset 256
		.amdhsa_reserve_vcc 1
		.amdhsa_float_round_mode_32 0
		.amdhsa_float_round_mode_16_64 0
		.amdhsa_float_denorm_mode_32 3
		.amdhsa_float_denorm_mode_16_64 3
		.amdhsa_dx10_clamp 1
		.amdhsa_ieee_mode 1
		.amdhsa_fp16_overflow 0
		.amdhsa_tg_split 0
		.amdhsa_exception_fp_ieee_invalid_op 0
		.amdhsa_exception_fp_denorm_src 0
		.amdhsa_exception_fp_ieee_div_zero 0
		.amdhsa_exception_fp_ieee_overflow 0
		.amdhsa_exception_fp_ieee_underflow 0
		.amdhsa_exception_fp_ieee_inexact 0
		.amdhsa_exception_int_div_zero 0
	.end_amdhsa_kernel

amdhsa.kernels:
  - .agpr_count:     0
    .args:
      - .offset:         0
        .size:           248
        .value_kind:     by_value
      - .offset:         248
        .size:           4
        .value_kind:     hidden_block_count_x
      - .offset:         252
        .size:           4
        .value_kind:     hidden_block_count_y
      - .offset:         256
        .size:           4
        .value_kind:     hidden_block_count_z
      - .offset:         260
        .size:           2
        .value_kind:     hidden_group_size_x
      - .offset:         262
        .size:           2
        .value_kind:     hidden_group_size_y
      - .offset:         264
        .size:           2
        .value_kind:     hidden_group_size_z
      - .offset:         266
        .size:           2
        .value_kind:     hidden_remainder_x
      - .offset:         268
        .size:           2
        .value_kind:     hidden_remainder_y
      - .offset:         270
        .size:           2
        .value_kind:     hidden_remainder_z
      - .offset:         288
        .size:           8
        .value_kind:     hidden_global_offset_x
      - .offset:         296
        .size:           8
        .value_kind:     hidden_global_offset_y
      - .offset:         304
        .size:           8
        .value_kind:     hidden_global_offset_z
      - .offset:         312
        .size:           2
        .value_kind:     hidden_grid_dims
      - .offset:         336
        .size:           8
        .value_kind:     hidden_multigrid_sync_arg
      - .offset:         368
        .size:           4
        .value_kind:     hidden_dynamic_lds_size
    .group_segment_fixed_size: 0
    .kernarg_segment_align: 8
    .kernarg_segment_size: 504
    .language:       OpenCL C
    .language_version:
      - 2
      - 0
    .max_flat_workgroup_size: 512
    .name:           _Z8yoco_fwd6Params
    .private_segment_fixed_size: 0
    .sgpr_count:     106
    .sgpr_spill_count: 359
    .symbol:         _Z8yoco_fwd6Params.kd
    .uniform_work_group_size: 1
    .uses_dynamic_stack: false
    .vgpr_count:     256
    .vgpr_spill_count: 0
    .wavefront_size: 64
